# speedup vs baseline: 1.0474x; 1.0047x over previous
; #define BJOB(C, POS, W1) for (int kc = lbid(); kc < 16; kc += gridDim.x) { const int n = ltid(); float s = 0.f; \
;     for (int k = kc * 128; k < kc * 128 + 128; ++k) s += (POS)[k] * (W1)[(long)k * 256 + n]; p.bias_part[((C) * 16 + kc) * 256 + n] = s; }
; DI void prep_phase(const Params& p, char* smem) {
;     ...
;   BJOB(0, p.a_pos_k, p.a_w1_k)
;   BJOB(1, p.a_pos_v, p.a_w1_v)
.LBB0_135:
	s_sub_i32 s15, s43, 16
	s_cmp_lt_u32 s14, 32
	s_cselect_b32 s15, s43, s15
	s_cmp_gt_u32 s15, 15
	s_cbranch_scc1 .LBB0_140
	s_load_dwordx2 s[0:1], s[56:57], 0x30
	s_load_dwordx2 s[4:5], s[56:57], 0x48
	s_load_dwordx2 s[6:7], s[56:57], 0xf8
	s_lshl_b32 s8, s15, 7
	s_add_i32 s16, s8, -1
	s_lshl_b32 s17, s14, 7
	v_mov_b32_e32 v4, 0
	s_mov_b64 s[10:11], 0x1000

; DI unsigned pack2(float a, float b) { v2f f = {a, b}; return __builtin_bit_cast(unsigned, __builtin_convertvector(f, v2bf)); }
; DI float bflo(unsigned v) { return __uint_as_float(v << 16); }
; DI float bfhi(unsigned v) { return __uint_as_float(v & 0xffff0000u); }
; template <bool HI_BF, bool HO_BF>
; DI void post_phase(const u16* __restrict__ y, const void* hin_, void* hout_,
;                    const float* __restrict__ gpost, const float* __restrict__ gpre, u16* __restrict__ uout) {
;     ...
;   for (int row = gw; row < T_TOK; row += nw) {
;     float4 hv[4];
; #pragma unroll
;     for (int j = 0; j < 4; ++j) {
;       if (HI_BF) {
;         const u32x2 hb = *(const u32x2*)((const u16*)hin_ + (long)row * 1024 + 4 * lane + 256 * j);
;         hv[j] = make_float4(bflo(hb.x), bfhi(hb.x), bflo(hb.y), bfhi(hb.y));
;       } else hv[j] = *(const float4*)(hin + (long)row * 1024 + 4 * lane + 256 * j);
;     }
;     ...
;     if (uout) {
;       float ss = 0.f;
; #pragma unroll
;       for (int j = 0; j < 4; ++j) ss += hv[j].x * hv[j].x + hv[j].y * hv[j].y + hv[j].z * hv[j].z + hv[j].w * hv[j].w;
; #pragma unroll
;       for (int o = 32; o > 0; o >>= 1) ss += __shfl_xor(ss, o);
;       const float ri = rsqrtf(ss * (1.f / 1024.f) + RMS_EPS);
; #pragma unroll
;       for (int j = 0; j < 4; ++j) {
;         const float4 g = *(const float4*)(gpre + 4 * lane + 256 * j);
;         u32x2 v; v.x = pack2(hv[j].x * ri * g.x, hv[j].y * ri * g.y); v.y = pack2(hv[j].z * ri * g.z, hv[j].w * ri * g.w);
;         *(u32x2*)(uout + (long)row * 1024 + 4 * lane + 256 * j) = v;
;       }
.LBB0_153:
	s_and_b64 vcc, exec, s[4:5]
	s_cbranch_vccnz .LBB0_152
	global_load_dwordx4 v[16:19], v[2:3], off offset:-1024
	global_load_dwordx4 v[20:23], v[2:3], off offset:-2048
	global_load_dwordx4 v[24:27], v[2:3], off offset:1024
	global_load_dwordx4 v[28:31], v[2:3], off
	global_load_dwordx4 v[32:35], v[0:1], off
	global_load_dwordx4 v[36:39], v[0:1], off offset:1024
	global_load_dwordx4 v[40:43], v[0:1], off offset:2048
	global_load_dwordx4 v[44:47], v[0:1], off offset:3072
	v_cmp_lt_i32_e32 vcc, v10, v9
	s_waitcnt vmcnt(7)
	v_mov_b32_e32 v52, v16
	s_waitcnt vmcnt(6)
	v_mov_b32_e32 v53, v20
	v_cndmask_b32_e32 v48, v8, v10, vcc
	v_mov_b32_e32 v54, v17
	v_mov_b32_e32 v55, v21
	s_waitcnt vmcnt(5)
	v_mov_b32_e32 v60, v24
	s_waitcnt vmcnt(4)
	v_mov_b32_e32 v61, v28
	v_pk_mul_f32 v[52:53], v[52:53], v[52:53]
	v_lshlrev_b32_e32 v64, 2, v48
	v_mov_b32_e32 v48, v18
	v_mov_b32_e32 v49, v22
	v_mov_b32_e32 v62, v25
	v_mov_b32_e32 v63, v29
	v_pk_mul_f32 v[60:61], v[60:61], v[60:61]
	v_pk_fma_f32 v[52:53], v[54:55], v[54:55], v[52:53]
	v_mov_b32_e32 v50, v19
	v_mov_b32_e32 v51, v23
	v_mov_b32_e32 v56, v26
	v_mov_b32_e32 v57, v30
	v_pk_fma_f32 v[54:55], v[62:63], v[62:63], v[60:61]
	v_pk_fma_f32 v[48:49], v[48:49], v[48:49], v[52:53]
	v_mov_b32_e32 v58, v27
	v_mov_b32_e32 v59, v31
	v_pk_fma_f32 v[52:53], v[56:57], v[56:57], v[54:55]
	v_pk_fma_f32 v[48:49], v[50:51], v[50:51], v[48:49]
	v_pk_fma_f32 v[50:51], v[58:59], v[58:59], v[52:53]
	v_add_f32_e32 v48, v48, v49
	v_add_f32_e32 v48, v51, v48
	v_add_f32_e32 v48, v50, v48
	v_mov_b32_e32 v49, v48
	s_nop 1
	v_permlane32_swap_b32_e32 v49, v48
	v_add_f32_e32 v48, v48, v49
	v_mov_b32_e32 v49, v48
	s_nop 1
	v_permlane16_swap_b32_e32 v49, v48
	v_add_f32_e32 v48, v48, v49
	s_nop 1
	v_add_f32_dpp v48, v48, v48 row_ror:8 row_mask:0xf bank_mask:0xf
	s_nop 1
	v_add_f32_dpp v100, v48, v48 row_shl:4 row_mask:0xf bank_mask:0x5
	v_add_f32_dpp v100, v48, v48 row_shr:4 row_mask:0xf bank_mask:0xa
	s_nop 1
	v_add_f32_dpp v48, v100, v100 quad_perm:[2,3,0,1] row_mask:0xf bank_mask:0xf
	s_nop 1
	v_add_f32_dpp v48, v48, v48 quad_perm:[1,0,3,2] row_mask:0xf bank_mask:0xf
	s_waitcnt lgkmcnt(0)
	s_nop 0
	v_fmamk_f32 v48, v48, 0x3a800000, v7
	v_mul_f32_e32 v49, 0x4b800000, v48
	v_cmp_gt_f32_e32 vcc, s0, v48
	s_nop 1
	v_cndmask_b32_e32 v48, v48, v49, vcc
	v_rsq_f32_e32 v48, v48
	s_nop 0
	v_mul_f32_e32 v49, 0x45800000, v48
	v_cndmask_b32_e32 v48, v48, v49, vcc
	v_pk_mul_f32 v[20:21], v[20:21], v[48:49] op_sel_hi:[1,0]
	v_pk_mul_f32 v[22:23], v[22:23], v[48:49] op_sel_hi:[1,0]
	v_pk_mul_f32 v[16:17], v[16:17], v[48:49] op_sel_hi:[1,0]
	v_pk_mul_f32 v[18:19], v[18:19], v[48:49] op_sel_hi:[1,0]
	v_pk_mul_f32 v[28:29], v[28:29], v[48:49] op_sel_hi:[1,0]
	v_pk_mul_f32 v[30:31], v[30:31], v[48:49] op_sel_hi:[1,0]
	v_pk_mul_f32 v[24:25], v[24:25], v[48:49] op_sel_hi:[1,0]
	v_pk_mul_f32 v[26:27], v[26:27], v[48:49] op_sel_hi:[1,0]
	s_waitcnt vmcnt(3)
	v_pk_mul_f32 v[20:21], v[32:33], v[20:21]
	v_pk_mul_f32 v[22:23], v[34:35], v[22:23]
	s_waitcnt vmcnt(2)
	v_pk_mul_f32 v[16:17], v[36:37], v[16:17]
	v_pk_mul_f32 v[18:19], v[38:39], v[18:19]
	s_waitcnt vmcnt(1)
	v_pk_mul_f32 v[28:29], v[40:41], v[28:29]
	v_pk_mul_f32 v[30:31], v[42:43], v[30:31]
	s_waitcnt vmcnt(0)
	v_pk_mul_f32 v[24:25], v[24:25], v[44:45]
	v_pk_mul_f32 v[26:27], v[26:27], v[46:47]
	v_cvt_pk_bf16_f32 v20, v20, v21
	v_cvt_pk_bf16_f32 v21, v22, v23
	v_cvt_pk_bf16_f32 v16, v16, v17
	v_cvt_pk_bf16_f32 v17, v18, v19
	v_cvt_pk_bf16_f32 v18, v28, v29
	v_cvt_pk_bf16_f32 v19, v30, v31
	v_cvt_pk_bf16_f32 v22, v24, v25
	v_cvt_pk_bf16_f32 v23, v26, v27
	global_store_dwordx2 v[4:5], v[20:21], off offset:-1024
	global_store_dwordx2 v[4:5], v[16:17], off offset:-512
	global_store_dwordx2 v[4:5], v[18:19], off
	global_store_dwordx2 v[4:5], v[22:23], off offset:512
	s_branch .LBB0_152

; DI float bflo(unsigned v) { return __uint_as_float(v << 16); }
; DI float bfhi(unsigned v) { return __uint_as_float(v & 0xffff0000u); }
; template <bool HI_BF, bool HO_BF>
; DI void post_phase(const u16* __restrict__ y, const void* hin_, void* hout_,
;                    const float* __restrict__ gpost, const float* __restrict__ gpre, u16* __restrict__ uout) {
;     ...
;   for (int row = gw; row < T_TOK; row += nw) {
;     float4 hv[4];
; #pragma unroll
;     for (int j = 0; j < 4; ++j) {
;       if (HI_BF) {
;         const u32x2 hb = *(const u32x2*)((const u16*)hin_ + (long)row * 1024 + 4 * lane + 256 * j);
;         hv[j] = make_float4(bflo(hb.x), bfhi(hb.x), bflo(hb.y), bfhi(hb.y));
;       } else hv[j] = *(const float4*)(hin + (long)row * 1024 + 4 * lane + 256 * j);
;     }
;     if (y) {
;       float4 yv[4]; float ss = 0.f;
; #pragma unroll
;       for (int j = 0; j < 4; ++j) {
;         const u32x2 yb = *(const u32x2*)(y + (long)row * 1024 + 4 * lane + 256 * j);
;         yv[j] = make_float4(bflo(yb.x), bfhi(yb.x), bflo(yb.y), bfhi(yb.y));
;         ss += yv[j].x * yv[j].x + yv[j].y * yv[j].y + yv[j].z * yv[j].z + yv[j].w * yv[j].w;
;       }
; #pragma unroll
;       for (int o = 32; o > 0; o >>= 1) ss += __shfl_xor(ss, o);
;       const float ri = rsqrtf(ss * (1.f / 1024.f) + RMS_EPS);
; #pragma unroll
;       for (int j = 0; j < 4; ++j) {
;         const float4 g = *(const float4*)(gpost + 4 * lane + 256 * j);
;         hv[j].x += yv[j].x * ri * g.x; hv[j].y += yv[j].y * ri * g.y; hv[j].z += yv[j].z * ri * g.z; hv[j].w += yv[j].w * ri * g.w;
;       }
;     }
.LBB0_1105:
	global_load_dwordx4 v[8:11], v[22:23], off offset:-2048
	global_load_dwordx4 v[12:15], v[22:23], off offset:-1024
	global_load_dwordx4 v[4:7], v[22:23], off
	global_load_dwordx4 v[0:3], v[22:23], off offset:1024
	s_and_b64 vcc, exec, s[4:5]
	v_cmp_lt_i32_e64 s[20:21], v34, v33
	v_cmp_lt_i32_e64 s[18:19], v35, v33
	v_cmp_lt_i32_e64 s[16:17], v36, v33
	v_cmp_lt_i32_e64 s[14:15], v37, v33
	v_cmp_lt_i32_e64 s[12:13], v38, v33
	v_cmp_lt_i32_e64 s[10:11], v39, v33
	s_cbranch_vccnz .LBB0_1107
	v_lshl_add_u64 v[40:41], v[26:27], 0, v[16:17]
	global_load_dwordx2 v[56:57], v[40:41], off
	global_load_dwordx2 v[58:59], v[40:41], off offset:512
	global_load_dwordx2 v[60:61], v[40:41], off offset:1024
	global_load_dwordx2 v[62:63], v[40:41], off offset:1536
	s_nop 0
	global_load_dwordx4 v[40:43], v[18:19], off
	global_load_dwordx4 v[44:47], v[18:19], off offset:1024
	global_load_dwordx4 v[48:51], v[18:19], off offset:2048
	global_load_dwordx4 v[52:55], v[18:19], off offset:3072
	v_cndmask_b32_e64 v64, v32, v34, s[20:21]
	v_lshlrev_b32_e32 v88, 2, v64
	s_waitcnt vmcnt(7)
	v_and_b32_e32 v67, 0xffff0000, v56
	s_waitcnt vmcnt(6)
	v_and_b32_e32 v69, 0xffff0000, v58
	v_lshlrev_b32_e32 v66, 16, v56
	v_lshlrev_b32_e32 v68, 16, v58
	s_waitcnt vmcnt(5)
	v_and_b32_e32 v71, 0xffff0000, v60
	s_waitcnt vmcnt(4)
	v_and_b32_e32 v73, 0xffff0000, v62
	v_mov_b32_e32 v78, v67
	v_mov_b32_e32 v79, v69
	v_lshlrev_b32_e32 v64, 16, v57
	v_lshlrev_b32_e32 v56, 16, v59
	v_lshlrev_b32_e32 v70, 16, v60
	v_lshlrev_b32_e32 v72, 16, v62
	v_mov_b32_e32 v76, v66
	v_mov_b32_e32 v77, v68
	v_mov_b32_e32 v86, v71
	v_mov_b32_e32 v87, v73
	v_pk_mul_f32 v[78:79], v[78:79], v[78:79]
	v_and_b32_e32 v65, 0xffff0000, v57
	v_and_b32_e32 v57, 0xffff0000, v59
	v_lshlrev_b32_e32 v58, 16, v61
	v_and_b32_e32 v59, 0xffff0000, v61
	v_lshlrev_b32_e32 v60, 16, v63
	v_and_b32_e32 v61, 0xffff0000, v63
	v_mov_b32_e32 v62, v64
	v_mov_b32_e32 v63, v56
	v_mov_b32_e32 v84, v70
	v_mov_b32_e32 v85, v72
	v_pk_mul_f32 v[86:87], v[86:87], v[86:87]
	v_pk_fma_f32 v[76:77], v[76:77], v[76:77], v[78:79]
	v_mov_b32_e32 v74, v65
	v_mov_b32_e32 v75, v57
	v_mov_b32_e32 v80, v58
	v_mov_b32_e32 v81, v60
	v_pk_fma_f32 v[78:79], v[84:85], v[84:85], v[86:87]
	v_pk_fma_f32 v[62:63], v[62:63], v[62:63], v[76:77]
	v_mov_b32_e32 v82, v59
	v_mov_b32_e32 v83, v61
	v_pk_fma_f32 v[76:77], v[80:81], v[80:81], v[78:79]
	v_pk_fma_f32 v[62:63], v[74:75], v[74:75], v[62:63]
	v_pk_fma_f32 v[74:75], v[82:83], v[82:83], v[76:77]
	v_add_f32_e32 v62, v62, v63
	v_add_f32_e32 v62, v62, v74
	v_add_f32_e32 v62, v62, v75
	v_mov_b32_e32 v63, v62
	s_nop 1
	v_permlane32_swap_b32_e32 v63, v62
	v_add_f32_e32 v62, v62, v63
	v_mov_b32_e32 v63, v62
	s_nop 1
	v_permlane16_swap_b32_e32 v63, v62
	v_add_f32_e32 v62, v62, v63
	s_nop 1
	v_add_f32_dpp v62, v62, v62 row_ror:8 row_mask:0xf bank_mask:0xf
	s_nop 1
	v_add_f32_dpp v100, v62, v62 row_shl:4 row_mask:0xf bank_mask:0x5
	v_add_f32_dpp v100, v62, v62 row_shr:4 row_mask:0xf bank_mask:0xa
	s_nop 1
	v_add_f32_dpp v62, v100, v100 quad_perm:[2,3,0,1] row_mask:0xf bank_mask:0xf
	s_nop 1
	v_add_f32_dpp v62, v62, v62 quad_perm:[1,0,3,2] row_mask:0xf bank_mask:0xf
	s_waitcnt lgkmcnt(0)
	s_nop 0
	v_fmamk_f32 v62, v62, 0x3a800000, v31
	v_mul_f32_e32 v63, 0x4b800000, v62
	v_cmp_gt_f32_e32 vcc, s0, v62
	s_nop 1
	v_cndmask_b32_e32 v62, v62, v63, vcc
	v_rsq_f32_e32 v62, v62
	s_nop 0
	v_mul_f32_e32 v63, 0x45800000, v62
	v_cndmask_b32_e32 v62, v62, v63, vcc
	v_pk_mul_f32 v[66:67], v[62:63], v[66:67] op_sel_hi:[0,1]
	v_pk_mul_f32 v[64:65], v[62:63], v[64:65] op_sel_hi:[0,1]
	v_pk_mul_f32 v[68:69], v[62:63], v[68:69] op_sel_hi:[0,1]
	v_pk_mul_f32 v[56:57], v[62:63], v[56:57] op_sel_hi:[0,1]
	v_pk_mul_f32 v[70:71], v[62:63], v[70:71] op_sel_hi:[0,1]
	v_pk_mul_f32 v[58:59], v[62:63], v[58:59] op_sel_hi:[0,1]
	v_pk_mul_f32 v[72:73], v[62:63], v[72:73] op_sel_hi:[0,1]
	v_pk_mul_f32 v[60:61], v[62:63], v[60:61] op_sel_hi:[0,1]
	s_waitcnt vmcnt(3)
	v_pk_fma_f32 v[8:9], v[40:41], v[66:67], v[8:9]
	v_pk_fma_f32 v[10:11], v[42:43], v[64:65], v[10:11]
	s_waitcnt vmcnt(2)
	v_pk_fma_f32 v[12:13], v[44:45], v[68:69], v[12:13]
	v_pk_fma_f32 v[14:15], v[46:47], v[56:57], v[14:15]
	s_waitcnt vmcnt(1)
	v_pk_fma_f32 v[4:5], v[48:49], v[70:71], v[4:5]
	v_pk_fma_f32 v[6:7], v[50:51], v[58:59], v[6:7]
	s_waitcnt vmcnt(0)
	v_pk_fma_f32 v[0:1], v[52:53], v[72:73], v[0:1]
	v_pk_fma_f32 v[2:3], v[54:55], v[60:61], v[2:3]

; DI unsigned pack2(float a, float b) { v2f f = {a, b}; return __builtin_bit_cast(unsigned, __builtin_convertvector(f, v2bf)); }
; template <bool HI_BF, bool HO_BF>
; DI void post_phase(const u16* __restrict__ y, const void* hin_, void* hout_,
;                    const float* __restrict__ gpost, const float* __restrict__ gpre, u16* __restrict__ uout) {
;     ...
;     if (hout_) {
; #pragma unroll
;       for (int j = 0; j < 4; ++j) {
;         if (HO_BF) { u32x2 v; v.x = pack2(hv[j].x, hv[j].y); v.y = pack2(hv[j].z, hv[j].w); *(u32x2*)((u16*)hout_ + (long)row * 1024 + 4 * lane + 256 * j) = v; }
;         else *(float4*)(hout + (long)row * 1024 + 4 * lane + 256 * j) = hv[j];
;       }
;     }
;     if (uout) {
;       float ss = 0.f;
; #pragma unroll
;       for (int j = 0; j < 4; ++j) ss += hv[j].x * hv[j].x + hv[j].y * hv[j].y + hv[j].z * hv[j].z + hv[j].w * hv[j].w;
; #pragma unroll
;       for (int o = 32; o > 0; o >>= 1) ss += __shfl_xor(ss, o);
;       const float ri = rsqrtf(ss * (1.f / 1024.f) + RMS_EPS);
; #pragma unroll
;       for (int j = 0; j < 4; ++j) {
;         const float4 g = *(const float4*)(gpre + 4 * lane + 256 * j);
;         u32x2 v; v.x = pack2(hv[j].x * ri * g.x, hv[j].y * ri * g.y); v.y = pack2(hv[j].z * ri * g.z, hv[j].w * ri * g.w);
;         *(u32x2*)(uout + (long)row * 1024 + 4 * lane + 256 * j) = v;
;       }
.LBB0_1109:
	s_and_b64 vcc, exec, s[8:9]
	s_cbranch_vccnz .LBB0_1104
	s_waitcnt vmcnt(3)
	v_mov_b32_e32 v42, v9
	s_waitcnt vmcnt(2)
	v_mov_b32_e32 v43, v13
	v_mov_b32_e32 v40, v8
	v_mov_b32_e32 v41, v12
	v_pk_mul_f32 v[42:43], v[42:43], v[42:43]
	s_waitcnt vmcnt(1)
	v_mov_b32_e32 v50, v5
	s_waitcnt vmcnt(0)
	v_mov_b32_e32 v51, v1
	v_pk_fma_f32 v[40:41], v[40:41], v[40:41], v[42:43]
	v_mov_b32_e32 v42, v10
	v_mov_b32_e32 v43, v14
	v_mov_b32_e32 v48, v4
	v_mov_b32_e32 v49, v0
	v_pk_mul_f32 v[50:51], v[50:51], v[50:51]
	v_pk_fma_f32 v[40:41], v[42:43], v[42:43], v[40:41]
	v_mov_b32_e32 v42, v11
	v_mov_b32_e32 v43, v15
	v_pk_fma_f32 v[48:49], v[48:49], v[48:49], v[50:51]
	v_mov_b32_e32 v50, v6
	v_mov_b32_e32 v51, v2
	v_pk_fma_f32 v[52:53], v[42:43], v[42:43], v[40:41]
	v_pk_fma_f32 v[54:55], v[50:51], v[50:51], v[48:49]
	v_mov_b32_e32 v56, v7
	v_mov_b32_e32 v57, v3
	v_pk_fma_f32 v[54:55], v[56:57], v[56:57], v[54:55]
	v_add_f32_e32 v52, v52, v53
	v_add_f32_e32 v52, v52, v54
	global_load_dwordx4 v[40:43], v[20:21], off
	global_load_dwordx4 v[44:47], v[20:21], off offset:1024
	global_load_dwordx4 v[48:51], v[20:21], off offset:2048
	v_add_f32_e32 v56, v52, v55
	global_load_dwordx4 v[52:55], v[20:21], off offset:3072
	v_cmp_lt_i32_e32 vcc, v34, v33
	s_nop 1
	v_cndmask_b32_e32 v57, v32, v34, vcc
	v_lshlrev_b32_e32 v57, 2, v57
	v_mov_b32_e32 v57, v56
	s_nop 1
	v_permlane32_swap_b32_e32 v57, v56
	v_add_f32_e32 v56, v56, v57
	v_mov_b32_e32 v57, v56
	s_nop 1
	v_permlane16_swap_b32_e32 v57, v56
	v_add_f32_e32 v56, v56, v57
	s_nop 1
	v_add_f32_dpp v56, v56, v56 row_ror:8 row_mask:0xf bank_mask:0xf
	s_nop 1
	v_add_f32_dpp v100, v56, v56 row_shl:4 row_mask:0xf bank_mask:0x5
	v_add_f32_dpp v100, v56, v56 row_shr:4 row_mask:0xf bank_mask:0xa
	s_nop 1
	v_add_f32_dpp v56, v100, v100 quad_perm:[2,3,0,1] row_mask:0xf bank_mask:0xf
	s_nop 1
	v_add_f32_dpp v56, v56, v56 quad_perm:[1,0,3,2] row_mask:0xf bank_mask:0xf
	s_waitcnt lgkmcnt(0)
	s_nop 0
	v_fmamk_f32 v56, v56, 0x3a800000, v31
	v_mul_f32_e32 v57, 0x4b800000, v56
	v_cmp_gt_f32_e32 vcc, s0, v56
	s_nop 1
	v_cndmask_b32_e32 v56, v56, v57, vcc
	v_rsq_f32_e32 v58, v56
	v_lshl_add_u64 v[56:57], v[24:25], 0, v[16:17]
	v_mul_f32_e32 v59, 0x45800000, v58
	v_cndmask_b32_e32 v58, v58, v59, vcc
	v_pk_mul_f32 v[8:9], v[8:9], v[58:59] op_sel_hi:[1,0]
	v_pk_mul_f32 v[10:11], v[10:11], v[58:59] op_sel_hi:[1,0]
	v_pk_mul_f32 v[4:5], v[4:5], v[58:59] op_sel_hi:[1,0]
	v_pk_mul_f32 v[6:7], v[6:7], v[58:59] op_sel_hi:[1,0]
	v_pk_mul_f32 v[0:1], v[0:1], v[58:59] op_sel_hi:[1,0]
	v_pk_mul_f32 v[2:3], v[2:3], v[58:59] op_sel_hi:[1,0]
	v_pk_mul_f32 v[12:13], v[12:13], v[58:59] op_sel_hi:[1,0]
	v_pk_mul_f32 v[14:15], v[14:15], v[58:59] op_sel_hi:[1,0]
	s_waitcnt vmcnt(3)
	v_pk_mul_f32 v[8:9], v[40:41], v[8:9]
	v_pk_mul_f32 v[10:11], v[42:43], v[10:11]
	s_waitcnt vmcnt(1)
	v_pk_mul_f32 v[4:5], v[4:5], v[48:49]
	v_pk_mul_f32 v[6:7], v[6:7], v[50:51]
	s_waitcnt vmcnt(0)
	v_pk_mul_f32 v[0:1], v[0:1], v[52:53]
	v_pk_mul_f32 v[2:3], v[2:3], v[54:55]
	v_pk_mul_f32 v[12:13], v[44:45], v[12:13]
	v_pk_mul_f32 v[14:15], v[46:47], v[14:15]
	v_cvt_pk_bf16_f32 v8, v8, v9
	v_cvt_pk_bf16_f32 v9, v10, v11
	v_cvt_pk_bf16_f32 v4, v4, v5
	v_cvt_pk_bf16_f32 v5, v6, v7
	v_cvt_pk_bf16_f32 v0, v0, v1
	v_cvt_pk_bf16_f32 v1, v2, v3
	v_cvt_pk_bf16_f32 v10, v12, v13
	v_cvt_pk_bf16_f32 v11, v14, v15
	global_store_dwordx2 v[56:57], v[8:9], off
	global_store_dwordx2 v[56:57], v[10:11], off offset:512
	global_store_dwordx2 v[56:57], v[4:5], off offset:1024
	global_store_dwordx2 v[56:57], v[0:1], off offset:1536
	s_branch .LBB0_1104

; DI float bflo(unsigned v) { return __uint_as_float(v << 16); }
; DI float bfhi(unsigned v) { return __uint_as_float(v & 0xffff0000u); }
; template <bool HI_BF, bool HO_BF>
; DI void post_phase(const u16* __restrict__ y, const void* hin_, void* hout_,
;                    const float* __restrict__ gpost, const float* __restrict__ gpre, u16* __restrict__ uout) {
;     ...
;   for (int row = gw; row < T_TOK; row += nw) {
;     float4 hv[4];
; #pragma unroll
;     for (int j = 0; j < 4; ++j) {
;       if (HI_BF) {
;         const u32x2 hb = *(const u32x2*)((const u16*)hin_ + (long)row * 1024 + 4 * lane + 256 * j);
;         hv[j] = make_float4(bflo(hb.x), bfhi(hb.x), bflo(hb.y), bfhi(hb.y));
;       } else hv[j] = *(const float4*)(hin + (long)row * 1024 + 4 * lane + 256 * j);
;     }
;     if (y) {
;       float4 yv[4]; float ss = 0.f;
; #pragma unroll
;       for (int j = 0; j < 4; ++j) {
;         const u32x2 yb = *(const u32x2*)(y + (long)row * 1024 + 4 * lane + 256 * j);
;         yv[j] = make_float4(bflo(yb.x), bfhi(yb.x), bflo(yb.y), bfhi(yb.y));
;         ss += yv[j].x * yv[j].x + yv[j].y * yv[j].y + yv[j].z * yv[j].z + yv[j].w * yv[j].w;
;       }
; #pragma unroll
;       for (int o = 32; o > 0; o >>= 1) ss += __shfl_xor(ss, o);
;       const float ri = rsqrtf(ss * (1.f / 1024.f) + RMS_EPS);
; #pragma unroll
;       for (int j = 0; j < 4; ++j) {
;         const float4 g = *(const float4*)(gpost + 4 * lane + 256 * j);
;         hv[j].x += yv[j].x * ri * g.x; hv[j].y += yv[j].y * ri * g.y; hv[j].z += yv[j].z * ri * g.z; hv[j].w += yv[j].w * ri * g.w;
;       }
;     }
.LBB0_1635:
	v_lshl_add_u64 v[28:29], v[8:9], 0, v[0:1]
	global_load_dwordx2 v[12:13], v[28:29], off
	global_load_dwordx2 v[14:15], v[28:29], off offset:512
	global_load_dwordx2 v[16:17], v[28:29], off offset:1024
	global_load_dwordx2 v[40:41], v[28:29], off offset:1536
	s_and_b64 vcc, exec, s[4:5]
	v_cmp_lt_i32_e64 s[20:21], v34, v33
	v_cmp_lt_i32_e64 s[16:17], v35, v33
	v_cmp_lt_i32_e64 s[14:15], v36, v33
	v_cmp_lt_i32_e64 s[12:13], v37, v33
	v_cmp_lt_i32_e64 s[10:11], v38, v33
	v_cmp_lt_i32_e64 s[18:19], v39, v33
	s_waitcnt vmcnt(3)
	v_lshlrev_b32_e32 v20, 16, v12
	v_and_b32_e32 v21, 0xffff0000, v12
	v_lshlrev_b32_e32 v22, 16, v13
	v_and_b32_e32 v23, 0xffff0000, v13
	s_waitcnt vmcnt(2)
	v_lshlrev_b32_e32 v24, 16, v14
	v_and_b32_e32 v25, 0xffff0000, v14
	v_lshlrev_b32_e32 v26, 16, v15
	v_and_b32_e32 v27, 0xffff0000, v15
	s_waitcnt vmcnt(1)
	v_lshlrev_b32_e32 v18, 16, v16
	v_and_b32_e32 v19, 0xffff0000, v16
	v_lshlrev_b32_e32 v16, 16, v17
	v_and_b32_e32 v17, 0xffff0000, v17
	s_waitcnt vmcnt(0)
	v_lshlrev_b32_e32 v14, 16, v40
	v_and_b32_e32 v15, 0xffff0000, v40
	v_lshlrev_b32_e32 v12, 16, v41
	v_and_b32_e32 v13, 0xffff0000, v41
	s_cbranch_vccnz .LBB0_1637
	v_lshl_add_u64 v[40:41], v[10:11], 0, v[0:1]
	global_load_dwordx2 v[56:57], v[40:41], off
	global_load_dwordx2 v[58:59], v[40:41], off offset:512
	global_load_dwordx2 v[60:61], v[40:41], off offset:1024
	global_load_dwordx2 v[62:63], v[40:41], off offset:1536
	s_nop 0
	global_load_dwordx4 v[40:43], v[2:3], off
	global_load_dwordx4 v[44:47], v[2:3], off offset:1024
	global_load_dwordx4 v[48:51], v[2:3], off offset:2048
	global_load_dwordx4 v[52:55], v[2:3], off offset:3072
	v_cndmask_b32_e64 v64, v32, v34, s[20:21]
	v_lshlrev_b32_e32 v88, 2, v64
	s_waitcnt vmcnt(7)
	v_and_b32_e32 v67, 0xffff0000, v56
	s_waitcnt vmcnt(6)
	v_and_b32_e32 v69, 0xffff0000, v58
	v_lshlrev_b32_e32 v66, 16, v56
	v_lshlrev_b32_e32 v68, 16, v58
	s_waitcnt vmcnt(5)
	v_and_b32_e32 v71, 0xffff0000, v60
	s_waitcnt vmcnt(4)
	v_and_b32_e32 v73, 0xffff0000, v62
	v_mov_b32_e32 v78, v67
	v_mov_b32_e32 v79, v69
	v_lshlrev_b32_e32 v64, 16, v57
	v_lshlrev_b32_e32 v56, 16, v59
	v_lshlrev_b32_e32 v70, 16, v60
	v_lshlrev_b32_e32 v72, 16, v62
	v_mov_b32_e32 v76, v66
	v_mov_b32_e32 v77, v68
	v_mov_b32_e32 v86, v71
	v_mov_b32_e32 v87, v73
	v_pk_mul_f32 v[78:79], v[78:79], v[78:79]
	v_and_b32_e32 v65, 0xffff0000, v57
	v_and_b32_e32 v57, 0xffff0000, v59
	v_lshlrev_b32_e32 v58, 16, v61
	v_and_b32_e32 v59, 0xffff0000, v61
	v_lshlrev_b32_e32 v60, 16, v63
	v_and_b32_e32 v61, 0xffff0000, v63
	v_mov_b32_e32 v62, v64
	v_mov_b32_e32 v63, v56
	v_mov_b32_e32 v84, v70
	v_mov_b32_e32 v85, v72
	v_pk_mul_f32 v[86:87], v[86:87], v[86:87]
	v_pk_fma_f32 v[76:77], v[76:77], v[76:77], v[78:79]
	v_mov_b32_e32 v74, v65
	v_mov_b32_e32 v75, v57
	v_mov_b32_e32 v80, v58
	v_mov_b32_e32 v81, v60
	v_pk_fma_f32 v[78:79], v[84:85], v[84:85], v[86:87]
	v_pk_fma_f32 v[62:63], v[62:63], v[62:63], v[76:77]
	v_mov_b32_e32 v82, v59
	v_mov_b32_e32 v83, v61
	v_pk_fma_f32 v[76:77], v[80:81], v[80:81], v[78:79]
	v_pk_fma_f32 v[62:63], v[74:75], v[74:75], v[62:63]
	v_pk_fma_f32 v[74:75], v[82:83], v[82:83], v[76:77]
	v_add_f32_e32 v62, v62, v63
	v_add_f32_e32 v62, v62, v74
	v_add_f32_e32 v62, v62, v75
	v_mov_b32_e32 v63, v62
	s_nop 1
	v_permlane32_swap_b32_e32 v63, v62
	v_add_f32_e32 v62, v62, v63
	v_mov_b32_e32 v63, v62
	s_nop 1
	v_permlane16_swap_b32_e32 v63, v62
	v_add_f32_e32 v62, v62, v63
	s_nop 1
	v_add_f32_dpp v62, v62, v62 row_ror:8 row_mask:0xf bank_mask:0xf
	s_nop 1
	v_add_f32_dpp v100, v62, v62 row_shl:4 row_mask:0xf bank_mask:0x5
	v_add_f32_dpp v100, v62, v62 row_shr:4 row_mask:0xf bank_mask:0xa
	s_nop 1
	v_add_f32_dpp v62, v100, v100 quad_perm:[2,3,0,1] row_mask:0xf bank_mask:0xf
	s_nop 1
	v_add_f32_dpp v62, v62, v62 quad_perm:[1,0,3,2] row_mask:0xf bank_mask:0xf
	s_waitcnt lgkmcnt(0)
	s_nop 0
	v_fmamk_f32 v62, v62, 0x3a800000, v31
	v_mul_f32_e32 v63, 0x4b800000, v62
	v_cmp_gt_f32_e32 vcc, s0, v62
	s_nop 1
	v_cndmask_b32_e32 v62, v62, v63, vcc
	v_rsq_f32_e32 v62, v62
	s_nop 0
	v_mul_f32_e32 v63, 0x45800000, v62
	v_cndmask_b32_e32 v62, v62, v63, vcc
	v_pk_mul_f32 v[66:67], v[62:63], v[66:67] op_sel_hi:[0,1]
	v_pk_mul_f32 v[64:65], v[62:63], v[64:65] op_sel_hi:[0,1]
	v_pk_mul_f32 v[68:69], v[62:63], v[68:69] op_sel_hi:[0,1]
	v_pk_mul_f32 v[56:57], v[62:63], v[56:57] op_sel_hi:[0,1]
	v_pk_mul_f32 v[70:71], v[62:63], v[70:71] op_sel_hi:[0,1]
	v_pk_mul_f32 v[58:59], v[62:63], v[58:59] op_sel_hi:[0,1]
	v_pk_mul_f32 v[72:73], v[62:63], v[72:73] op_sel_hi:[0,1]
	v_pk_mul_f32 v[60:61], v[62:63], v[60:61] op_sel_hi:[0,1]
	s_waitcnt vmcnt(3)
	v_pk_fma_f32 v[20:21], v[40:41], v[66:67], v[20:21]
	v_pk_fma_f32 v[22:23], v[42:43], v[64:65], v[22:23]
	s_waitcnt vmcnt(2)
	v_pk_fma_f32 v[24:25], v[44:45], v[68:69], v[24:25]
	v_pk_fma_f32 v[26:27], v[46:47], v[56:57], v[26:27]
	s_waitcnt vmcnt(1)
	v_pk_fma_f32 v[18:19], v[48:49], v[70:71], v[18:19]
	v_pk_fma_f32 v[16:17], v[50:51], v[58:59], v[16:17]
	s_waitcnt vmcnt(0)
	v_pk_fma_f32 v[14:15], v[52:53], v[72:73], v[14:15]
	v_pk_fma_f32 v[12:13], v[54:55], v[60:61], v[12:13]

; DI unsigned pack2(float a, float b) { v2f f = {a, b}; return __builtin_bit_cast(unsigned, __builtin_convertvector(f, v2bf)); }
; template <bool HI_BF, bool HO_BF>
; DI void post_phase(const u16* __restrict__ y, const void* hin_, void* hout_,
;                    const float* __restrict__ gpost, const float* __restrict__ gpre, u16* __restrict__ uout) {
;     ...
;     if (hout_) {
; #pragma unroll
;       for (int j = 0; j < 4; ++j) {
;         if (HO_BF) { u32x2 v; v.x = pack2(hv[j].x, hv[j].y); v.y = pack2(hv[j].z, hv[j].w); *(u32x2*)((u16*)hout_ + (long)row * 1024 + 4 * lane + 256 * j) = v; }
;         else *(float4*)(hout + (long)row * 1024 + 4 * lane + 256 * j) = hv[j];
;       }
;     }
;     if (uout) {
;       float ss = 0.f;
; #pragma unroll
;       for (int j = 0; j < 4; ++j) ss += hv[j].x * hv[j].x + hv[j].y * hv[j].y + hv[j].z * hv[j].z + hv[j].w * hv[j].w;
; #pragma unroll
;       for (int o = 32; o > 0; o >>= 1) ss += __shfl_xor(ss, o);
;       const float ri = rsqrtf(ss * (1.f / 1024.f) + RMS_EPS);
; #pragma unroll
;       for (int j = 0; j < 4; ++j) {
;         const float4 g = *(const float4*)(gpre + 4 * lane + 256 * j);
;         u32x2 v; v.x = pack2(hv[j].x * ri * g.x, hv[j].y * ri * g.y); v.y = pack2(hv[j].z * ri * g.z, hv[j].w * ri * g.w);
;         *(u32x2*)(uout + (long)row * 1024 + 4 * lane + 256 * j) = v;
;       }
.LBB0_1639:
	s_and_b64 vcc, exec, s[8:9]
	s_cbranch_vccnz .LBB0_1634
	v_mov_b32_e32 v40, v21
	v_mov_b32_e32 v41, v25
	v_mov_b32_e32 v28, v20
	v_mov_b32_e32 v29, v24
	v_pk_mul_f32 v[40:41], v[40:41], v[40:41]
	v_mov_b32_e32 v50, v19
	v_mov_b32_e32 v51, v15
	v_pk_fma_f32 v[28:29], v[28:29], v[28:29], v[40:41]
	v_mov_b32_e32 v40, v22
	v_mov_b32_e32 v41, v26
	v_mov_b32_e32 v48, v18
	v_mov_b32_e32 v49, v14
	v_pk_mul_f32 v[50:51], v[50:51], v[50:51]
	v_pk_fma_f32 v[28:29], v[40:41], v[40:41], v[28:29]
	v_mov_b32_e32 v40, v23
	v_mov_b32_e32 v41, v27
	v_pk_fma_f32 v[48:49], v[48:49], v[48:49], v[50:51]
	v_mov_b32_e32 v50, v16
	v_mov_b32_e32 v51, v12
	v_pk_fma_f32 v[28:29], v[40:41], v[40:41], v[28:29]
	v_pk_fma_f32 v[52:53], v[50:51], v[50:51], v[48:49]
	v_mov_b32_e32 v54, v17
	v_mov_b32_e32 v55, v13
	v_pk_fma_f32 v[52:53], v[54:55], v[54:55], v[52:53]
	v_add_f32_e32 v28, v28, v29
	v_add_f32_e32 v28, v28, v52
	global_load_dwordx4 v[40:43], v[4:5], off
	global_load_dwordx4 v[44:47], v[4:5], off offset:1024
	global_load_dwordx4 v[48:51], v[4:5], off offset:2048
	v_add_f32_e32 v28, v28, v53
	global_load_dwordx4 v[52:55], v[4:5], off offset:3072
	v_cmp_lt_i32_e32 vcc, v34, v33
	s_nop 1
	v_cndmask_b32_e32 v29, v32, v34, vcc
	v_lshlrev_b32_e32 v29, 2, v29
	v_mov_b32_e32 v29, v28
	s_nop 1
	v_permlane32_swap_b32_e32 v29, v28
	v_add_f32_e32 v28, v28, v29
	v_mov_b32_e32 v29, v28
	s_nop 1
	v_permlane16_swap_b32_e32 v29, v28
	v_add_f32_e32 v28, v28, v29
	s_nop 1
	v_add_f32_dpp v28, v28, v28 row_ror:8 row_mask:0xf bank_mask:0xf
	s_nop 1
	v_add_f32_dpp v100, v28, v28 row_shl:4 row_mask:0xf bank_mask:0x5
	v_add_f32_dpp v100, v28, v28 row_shr:4 row_mask:0xf bank_mask:0xa
	s_nop 1
	v_add_f32_dpp v28, v100, v100 quad_perm:[2,3,0,1] row_mask:0xf bank_mask:0xf
	s_nop 1
	v_add_f32_dpp v28, v28, v28 quad_perm:[1,0,3,2] row_mask:0xf bank_mask:0xf
	s_waitcnt lgkmcnt(0)
	s_nop 0
	v_fmamk_f32 v28, v28, 0x3a800000, v31
	v_mul_f32_e32 v29, 0x4b800000, v28
	v_cmp_gt_f32_e32 vcc, s0, v28
	s_nop 1
	v_cndmask_b32_e32 v28, v28, v29, vcc
	v_rsq_f32_e32 v56, v28
	v_lshl_add_u64 v[28:29], v[6:7], 0, v[0:1]
	v_mul_f32_e32 v57, 0x45800000, v56
	v_cndmask_b32_e32 v56, v56, v57, vcc
	v_pk_mul_f32 v[20:21], v[20:21], v[56:57] op_sel_hi:[1,0]
	v_pk_mul_f32 v[22:23], v[22:23], v[56:57] op_sel_hi:[1,0]
	v_pk_mul_f32 v[18:19], v[18:19], v[56:57] op_sel_hi:[1,0]
	v_pk_mul_f32 v[16:17], v[16:17], v[56:57] op_sel_hi:[1,0]
	v_pk_mul_f32 v[14:15], v[14:15], v[56:57] op_sel_hi:[1,0]
	v_pk_mul_f32 v[12:13], v[12:13], v[56:57] op_sel_hi:[1,0]
	v_pk_mul_f32 v[24:25], v[24:25], v[56:57] op_sel_hi:[1,0]
	v_pk_mul_f32 v[26:27], v[26:27], v[56:57] op_sel_hi:[1,0]
	s_waitcnt vmcnt(3)
	v_pk_mul_f32 v[20:21], v[40:41], v[20:21]
	v_pk_mul_f32 v[22:23], v[42:43], v[22:23]
	s_waitcnt vmcnt(1)
	v_pk_mul_f32 v[18:19], v[18:19], v[48:49]
	v_pk_mul_f32 v[16:17], v[16:17], v[50:51]
	s_waitcnt vmcnt(0)
	v_pk_mul_f32 v[14:15], v[14:15], v[52:53]
	v_pk_mul_f32 v[12:13], v[12:13], v[54:55]
	v_pk_mul_f32 v[24:25], v[44:45], v[24:25]
	v_pk_mul_f32 v[26:27], v[46:47], v[26:27]
	v_cvt_pk_bf16_f32 v20, v20, v21
	v_cvt_pk_bf16_f32 v21, v22, v23
	v_cvt_pk_bf16_f32 v18, v18, v19
	v_cvt_pk_bf16_f32 v19, v16, v17
	v_cvt_pk_bf16_f32 v14, v14, v15
	v_cvt_pk_bf16_f32 v15, v12, v13
	v_cvt_pk_bf16_f32 v22, v24, v25
	v_cvt_pk_bf16_f32 v23, v26, v27
	global_store_dwordx2 v[28:29], v[20:21], off
	global_store_dwordx2 v[28:29], v[22:23], off offset:512
	global_store_dwordx2 v[28:29], v[18:19], off offset:1024
	global_store_dwordx2 v[28:29], v[14:15], off offset:1536
	s_branch .LBB0_1634

; DI float bflo(unsigned v) { return __uint_as_float(v << 16); }
; DI float bfhi(unsigned v) { return __uint_as_float(v & 0xffff0000u); }
; template <bool HI_BF, bool HO_BF>
; DI void post_phase(const u16* __restrict__ y, const void* hin_, void* hout_,
;                    const float* __restrict__ gpost, const float* __restrict__ gpre, u16* __restrict__ uout) {
;     ...
;   for (int row = gw; row < T_TOK; row += nw) {
;     float4 hv[4];
; #pragma unroll
;     for (int j = 0; j < 4; ++j) {
;       if (HI_BF) {
;         const u32x2 hb = *(const u32x2*)((const u16*)hin_ + (long)row * 1024 + 4 * lane + 256 * j);
;         hv[j] = make_float4(bflo(hb.x), bfhi(hb.x), bflo(hb.y), bfhi(hb.y));
;       } else hv[j] = *(const float4*)(hin + (long)row * 1024 + 4 * lane + 256 * j);
;     }
;     if (y) {
;       float4 yv[4]; float ss = 0.f;
; #pragma unroll
;       for (int j = 0; j < 4; ++j) {
;         const u32x2 yb = *(const u32x2*)(y + (long)row * 1024 + 4 * lane + 256 * j);
;         yv[j] = make_float4(bflo(yb.x), bfhi(yb.x), bflo(yb.y), bfhi(yb.y));
;         ss += yv[j].x * yv[j].x + yv[j].y * yv[j].y + yv[j].z * yv[j].z + yv[j].w * yv[j].w;
;       }
; #pragma unroll
;       for (int o = 32; o > 0; o >>= 1) ss += __shfl_xor(ss, o);
;       const float ri = rsqrtf(ss * (1.f / 1024.f) + RMS_EPS);
; #pragma unroll
;       for (int j = 0; j < 4; ++j) {
;         const float4 g = *(const float4*)(gpost + 4 * lane + 256 * j);
;         hv[j].x += yv[j].x * ri * g.x; hv[j].y += yv[j].y * ri * g.y; hv[j].z += yv[j].z * ri * g.z; hv[j].w += yv[j].w * ri * g.w;
;       }
;     }
.LBB0_2247:
	v_lshl_add_u64 v[14:15], v[8:9], 0, v[0:1]
	global_load_dwordx2 v[16:17], v[14:15], off
	global_load_dwordx2 v[18:19], v[14:15], off offset:512
	global_load_dwordx2 v[40:41], v[14:15], off offset:1024
	global_load_dwordx2 v[42:43], v[14:15], off offset:1536
	s_and_b64 vcc, exec, s[4:5]
	v_cmp_lt_i32_e64 s[20:21], v34, v33
	v_cmp_lt_i32_e64 s[16:17], v35, v33
	v_cmp_lt_i32_e64 s[14:15], v36, v33
	v_cmp_lt_i32_e64 s[12:13], v37, v33
	v_cmp_lt_i32_e64 s[10:11], v38, v33
	v_cmp_lt_i32_e64 s[18:19], v39, v33
	s_waitcnt vmcnt(3)
	v_lshlrev_b32_e32 v22, 16, v16
	v_and_b32_e32 v23, 0xffff0000, v16
	v_lshlrev_b32_e32 v24, 16, v17
	v_and_b32_e32 v25, 0xffff0000, v17
	s_waitcnt vmcnt(2)
	v_lshlrev_b32_e32 v26, 16, v18
	v_and_b32_e32 v27, 0xffff0000, v18
	v_lshlrev_b32_e32 v28, 16, v19
	v_and_b32_e32 v29, 0xffff0000, v19
	s_waitcnt vmcnt(1)
	v_lshlrev_b32_e32 v20, 16, v40
	v_and_b32_e32 v21, 0xffff0000, v40
	v_lshlrev_b32_e32 v18, 16, v41
	v_and_b32_e32 v19, 0xffff0000, v41
	s_waitcnt vmcnt(0)
	v_lshlrev_b32_e32 v16, 16, v42
	v_and_b32_e32 v17, 0xffff0000, v42
	v_lshlrev_b32_e32 v14, 16, v43
	v_and_b32_e32 v15, 0xffff0000, v43
	s_cbranch_vccnz .LBB0_2249
	v_lshl_add_u64 v[40:41], v[12:13], 0, v[0:1]
	global_load_dwordx2 v[56:57], v[40:41], off
	global_load_dwordx2 v[58:59], v[40:41], off offset:512
	global_load_dwordx2 v[60:61], v[40:41], off offset:1024
	global_load_dwordx2 v[62:63], v[40:41], off offset:1536
	s_nop 0
	global_load_dwordx4 v[40:43], v[2:3], off
	global_load_dwordx4 v[44:47], v[2:3], off offset:1024
	global_load_dwordx4 v[48:51], v[2:3], off offset:2048
	global_load_dwordx4 v[52:55], v[2:3], off offset:3072
	v_cndmask_b32_e64 v64, v32, v34, s[20:21]
	v_lshlrev_b32_e32 v88, 2, v64
	s_waitcnt vmcnt(7)
	v_and_b32_e32 v67, 0xffff0000, v56
	s_waitcnt vmcnt(6)
	v_and_b32_e32 v69, 0xffff0000, v58
	v_lshlrev_b32_e32 v66, 16, v56
	v_lshlrev_b32_e32 v68, 16, v58
	s_waitcnt vmcnt(5)
	v_and_b32_e32 v71, 0xffff0000, v60
	s_waitcnt vmcnt(4)
	v_and_b32_e32 v73, 0xffff0000, v62
	v_mov_b32_e32 v78, v67
	v_mov_b32_e32 v79, v69
	v_lshlrev_b32_e32 v64, 16, v57
	v_lshlrev_b32_e32 v56, 16, v59
	v_lshlrev_b32_e32 v70, 16, v60
	v_lshlrev_b32_e32 v72, 16, v62
	v_mov_b32_e32 v76, v66
	v_mov_b32_e32 v77, v68
	v_mov_b32_e32 v86, v71
	v_mov_b32_e32 v87, v73
	v_pk_mul_f32 v[78:79], v[78:79], v[78:79]
	v_and_b32_e32 v65, 0xffff0000, v57
	v_and_b32_e32 v57, 0xffff0000, v59
	v_lshlrev_b32_e32 v58, 16, v61
	v_and_b32_e32 v59, 0xffff0000, v61
	v_lshlrev_b32_e32 v60, 16, v63
	v_and_b32_e32 v61, 0xffff0000, v63
	v_mov_b32_e32 v62, v64
	v_mov_b32_e32 v63, v56
	v_mov_b32_e32 v84, v70
	v_mov_b32_e32 v85, v72
	v_pk_mul_f32 v[86:87], v[86:87], v[86:87]
	v_pk_fma_f32 v[76:77], v[76:77], v[76:77], v[78:79]
	v_mov_b32_e32 v74, v65
	v_mov_b32_e32 v75, v57
	v_mov_b32_e32 v80, v58
	v_mov_b32_e32 v81, v60
	v_pk_fma_f32 v[78:79], v[84:85], v[84:85], v[86:87]
	v_pk_fma_f32 v[62:63], v[62:63], v[62:63], v[76:77]
	v_mov_b32_e32 v82, v59
	v_mov_b32_e32 v83, v61
	v_pk_fma_f32 v[76:77], v[80:81], v[80:81], v[78:79]
	v_pk_fma_f32 v[62:63], v[74:75], v[74:75], v[62:63]
	v_pk_fma_f32 v[74:75], v[82:83], v[82:83], v[76:77]
	v_add_f32_e32 v62, v62, v63
	v_add_f32_e32 v62, v62, v74
	v_add_f32_e32 v62, v62, v75
	v_mov_b32_e32 v63, v62
	s_nop 1
	v_permlane32_swap_b32_e32 v63, v62
	v_add_f32_e32 v62, v62, v63
	v_mov_b32_e32 v63, v62
	s_nop 1
	v_permlane16_swap_b32_e32 v63, v62
	v_add_f32_e32 v62, v62, v63
	s_nop 1
	v_add_f32_dpp v62, v62, v62 row_ror:8 row_mask:0xf bank_mask:0xf
	s_nop 1
	v_add_f32_dpp v100, v62, v62 row_shl:4 row_mask:0xf bank_mask:0x5
	v_add_f32_dpp v100, v62, v62 row_shr:4 row_mask:0xf bank_mask:0xa
	s_nop 1
	v_add_f32_dpp v62, v100, v100 quad_perm:[2,3,0,1] row_mask:0xf bank_mask:0xf
	s_nop 1
	v_add_f32_dpp v62, v62, v62 quad_perm:[1,0,3,2] row_mask:0xf bank_mask:0xf
	s_waitcnt lgkmcnt(0)
	s_nop 0
	v_fmamk_f32 v62, v62, 0x3a800000, v31
	v_mul_f32_e32 v63, 0x4b800000, v62
	v_cmp_gt_f32_e32 vcc, s0, v62
	s_nop 1
	v_cndmask_b32_e32 v62, v62, v63, vcc
	v_rsq_f32_e32 v62, v62
	s_nop 0
	v_mul_f32_e32 v63, 0x45800000, v62
	v_cndmask_b32_e32 v62, v62, v63, vcc
	v_pk_mul_f32 v[66:67], v[62:63], v[66:67] op_sel_hi:[0,1]
	v_pk_mul_f32 v[64:65], v[62:63], v[64:65] op_sel_hi:[0,1]
	v_pk_mul_f32 v[68:69], v[62:63], v[68:69] op_sel_hi:[0,1]
	v_pk_mul_f32 v[56:57], v[62:63], v[56:57] op_sel_hi:[0,1]
	v_pk_mul_f32 v[70:71], v[62:63], v[70:71] op_sel_hi:[0,1]
	v_pk_mul_f32 v[58:59], v[62:63], v[58:59] op_sel_hi:[0,1]
	v_pk_mul_f32 v[72:73], v[62:63], v[72:73] op_sel_hi:[0,1]
	v_pk_mul_f32 v[60:61], v[62:63], v[60:61] op_sel_hi:[0,1]
	s_waitcnt vmcnt(3)
	v_pk_fma_f32 v[22:23], v[40:41], v[66:67], v[22:23]
	v_pk_fma_f32 v[24:25], v[42:43], v[64:65], v[24:25]
	s_waitcnt vmcnt(2)
	v_pk_fma_f32 v[26:27], v[44:45], v[68:69], v[26:27]
	v_pk_fma_f32 v[28:29], v[46:47], v[56:57], v[28:29]
	s_waitcnt vmcnt(1)
	v_pk_fma_f32 v[20:21], v[48:49], v[70:71], v[20:21]
	v_pk_fma_f32 v[18:19], v[50:51], v[58:59], v[18:19]
	s_waitcnt vmcnt(0)
	v_pk_fma_f32 v[16:17], v[52:53], v[72:73], v[16:17]
	v_pk_fma_f32 v[14:15], v[54:55], v[60:61], v[14:15]

; DI unsigned pack2(float a, float b) { v2f f = {a, b}; return __builtin_bit_cast(unsigned, __builtin_convertvector(f, v2bf)); }
; template <bool HI_BF, bool HO_BF>
; DI void post_phase(const u16* __restrict__ y, const void* hin_, void* hout_,
;                    const float* __restrict__ gpost, const float* __restrict__ gpre, u16* __restrict__ uout) {
;     ...
;     if (hout_) {
; #pragma unroll
;       for (int j = 0; j < 4; ++j) {
;         if (HO_BF) { u32x2 v; v.x = pack2(hv[j].x, hv[j].y); v.y = pack2(hv[j].z, hv[j].w); *(u32x2*)((u16*)hout_ + (long)row * 1024 + 4 * lane + 256 * j) = v; }
;         else *(float4*)(hout + (long)row * 1024 + 4 * lane + 256 * j) = hv[j];
;       }
;     }
;     if (uout) {
;       float ss = 0.f;
; #pragma unroll
;       for (int j = 0; j < 4; ++j) ss += hv[j].x * hv[j].x + hv[j].y * hv[j].y + hv[j].z * hv[j].z + hv[j].w * hv[j].w;
; #pragma unroll
;       for (int o = 32; o > 0; o >>= 1) ss += __shfl_xor(ss, o);
;       const float ri = rsqrtf(ss * (1.f / 1024.f) + RMS_EPS);
; #pragma unroll
;       for (int j = 0; j < 4; ++j) {
;         const float4 g = *(const float4*)(gpre + 4 * lane + 256 * j);
;         u32x2 v; v.x = pack2(hv[j].x * ri * g.x, hv[j].y * ri * g.y); v.y = pack2(hv[j].z * ri * g.z, hv[j].w * ri * g.w);
;         *(u32x2*)(uout + (long)row * 1024 + 4 * lane + 256 * j) = v;
;       }
.LBB0_2251:
	s_and_b64 vcc, exec, s[8:9]
	s_cbranch_vccnz .LBB0_2246
	v_mov_b32_e32 v42, v23
	v_mov_b32_e32 v43, v27
	v_mov_b32_e32 v40, v22
	v_mov_b32_e32 v41, v26
	v_pk_mul_f32 v[42:43], v[42:43], v[42:43]
	v_mov_b32_e32 v50, v21
	v_mov_b32_e32 v51, v17
	v_pk_fma_f32 v[40:41], v[40:41], v[40:41], v[42:43]
	v_mov_b32_e32 v42, v24
	v_mov_b32_e32 v43, v28
	v_mov_b32_e32 v48, v20
	v_mov_b32_e32 v49, v16
	v_pk_mul_f32 v[50:51], v[50:51], v[50:51]
	v_pk_fma_f32 v[40:41], v[42:43], v[42:43], v[40:41]
	v_mov_b32_e32 v42, v25
	v_mov_b32_e32 v43, v29
	v_pk_fma_f32 v[48:49], v[48:49], v[48:49], v[50:51]
	v_mov_b32_e32 v50, v18
	v_mov_b32_e32 v51, v14
	v_pk_fma_f32 v[52:53], v[42:43], v[42:43], v[40:41]
	v_pk_fma_f32 v[54:55], v[50:51], v[50:51], v[48:49]
	v_mov_b32_e32 v56, v19
	v_mov_b32_e32 v57, v15
	v_pk_fma_f32 v[54:55], v[56:57], v[56:57], v[54:55]
	v_add_f32_e32 v52, v52, v53
	v_add_f32_e32 v52, v52, v54
	global_load_dwordx4 v[40:43], v[4:5], off
	global_load_dwordx4 v[44:47], v[4:5], off offset:1024
	global_load_dwordx4 v[48:51], v[4:5], off offset:2048
	v_add_f32_e32 v56, v52, v55
	global_load_dwordx4 v[52:55], v[4:5], off offset:3072
	v_cmp_lt_i32_e32 vcc, v34, v33
	s_nop 1
	v_cndmask_b32_e32 v57, v32, v34, vcc
	v_lshlrev_b32_e32 v57, 2, v57
	v_mov_b32_e32 v57, v56
	s_nop 1
	v_permlane32_swap_b32_e32 v57, v56
	v_add_f32_e32 v56, v56, v57
	v_mov_b32_e32 v57, v56
	s_nop 1
	v_permlane16_swap_b32_e32 v57, v56
	v_add_f32_e32 v56, v56, v57
	s_nop 1
	v_add_f32_dpp v56, v56, v56 row_ror:8 row_mask:0xf bank_mask:0xf
	s_nop 1
	v_add_f32_dpp v100, v56, v56 row_shl:4 row_mask:0xf bank_mask:0x5
	v_add_f32_dpp v100, v56, v56 row_shr:4 row_mask:0xf bank_mask:0xa
	s_nop 1
	v_add_f32_dpp v56, v100, v100 quad_perm:[2,3,0,1] row_mask:0xf bank_mask:0xf
	s_nop 1
	v_add_f32_dpp v56, v56, v56 quad_perm:[1,0,3,2] row_mask:0xf bank_mask:0xf
	s_waitcnt lgkmcnt(0)
	s_nop 0
	v_fmamk_f32 v56, v56, 0x3a800000, v31
	v_mul_f32_e32 v57, 0x4b800000, v56
	v_cmp_gt_f32_e32 vcc, s0, v56
	s_nop 1
	v_cndmask_b32_e32 v56, v56, v57, vcc
	v_rsq_f32_e32 v58, v56
	v_lshl_add_u64 v[56:57], v[6:7], 0, v[0:1]
	v_mul_f32_e32 v59, 0x45800000, v58
	v_cndmask_b32_e32 v58, v58, v59, vcc
	v_pk_mul_f32 v[22:23], v[22:23], v[58:59] op_sel_hi:[1,0]
	v_pk_mul_f32 v[24:25], v[24:25], v[58:59] op_sel_hi:[1,0]
	v_pk_mul_f32 v[20:21], v[20:21], v[58:59] op_sel_hi:[1,0]
	v_pk_mul_f32 v[18:19], v[18:19], v[58:59] op_sel_hi:[1,0]
	v_pk_mul_f32 v[16:17], v[16:17], v[58:59] op_sel_hi:[1,0]
	v_pk_mul_f32 v[14:15], v[14:15], v[58:59] op_sel_hi:[1,0]
	v_pk_mul_f32 v[26:27], v[26:27], v[58:59] op_sel_hi:[1,0]
	v_pk_mul_f32 v[28:29], v[28:29], v[58:59] op_sel_hi:[1,0]
	s_waitcnt vmcnt(3)
	v_pk_mul_f32 v[22:23], v[40:41], v[22:23]
	v_pk_mul_f32 v[24:25], v[42:43], v[24:25]
	s_waitcnt vmcnt(1)
	v_pk_mul_f32 v[20:21], v[20:21], v[48:49]
	v_pk_mul_f32 v[18:19], v[18:19], v[50:51]
	s_waitcnt vmcnt(0)
	v_pk_mul_f32 v[16:17], v[16:17], v[52:53]
	v_pk_mul_f32 v[14:15], v[14:15], v[54:55]
	v_pk_mul_f32 v[26:27], v[44:45], v[26:27]
	v_pk_mul_f32 v[28:29], v[46:47], v[28:29]
	v_cvt_pk_bf16_f32 v22, v22, v23
	v_cvt_pk_bf16_f32 v23, v24, v25
	v_cvt_pk_bf16_f32 v20, v20, v21
	v_cvt_pk_bf16_f32 v21, v18, v19
	v_cvt_pk_bf16_f32 v16, v16, v17
	v_cvt_pk_bf16_f32 v17, v14, v15
	v_cvt_pk_bf16_f32 v24, v26, v27
	v_cvt_pk_bf16_f32 v25, v28, v29
	global_store_dwordx2 v[56:57], v[22:23], off
	global_store_dwordx2 v[56:57], v[24:25], off offset:512
	global_store_dwordx2 v[56:57], v[20:21], off offset:1024
	global_store_dwordx2 v[56:57], v[16:17], off offset:1536
	s_branch .LBB0_2246

; DI float bflo(unsigned v) { return __uint_as_float(v << 16); }
; DI float bfhi(unsigned v) { return __uint_as_float(v & 0xffff0000u); }
; template <bool HI_BF, bool HO_BF>
; DI void post_phase(const u16* __restrict__ y, const void* hin_, void* hout_,
;                    const float* __restrict__ gpost, const float* __restrict__ gpre, u16* __restrict__ uout) {
;     ...
; #pragma unroll
;     for (int j = 0; j < 4; ++j) {
;       if (HI_BF) {
;         const u32x2 hb = *(const u32x2*)((const u16*)hin_ + (long)row * 1024 + 4 * lane + 256 * j);
;         hv[j] = make_float4(bflo(hb.x), bfhi(hb.x), bflo(hb.y), bfhi(hb.y));
;       } else hv[j] = *(const float4*)(hin + (long)row * 1024 + 4 * lane + 256 * j);
;     }
;     if (y) {
;       float4 yv[4]; float ss = 0.f;
; #pragma unroll
;       for (int j = 0; j < 4; ++j) {
;         const u32x2 yb = *(const u32x2*)(y + (long)row * 1024 + 4 * lane + 256 * j);
;         yv[j] = make_float4(bflo(yb.x), bfhi(yb.x), bflo(yb.y), bfhi(yb.y));
;         ss += yv[j].x * yv[j].x + yv[j].y * yv[j].y + yv[j].z * yv[j].z + yv[j].w * yv[j].w;
;       }
; #pragma unroll
;       for (int o = 32; o > 0; o >>= 1) ss += __shfl_xor(ss, o);
;       const float ri = rsqrtf(ss * (1.f / 1024.f) + RMS_EPS);
; #pragma unroll
;       for (int j = 0; j < 4; ++j) {
;         const float4 g = *(const float4*)(gpost + 4 * lane + 256 * j);
;         hv[j].x += yv[j].x * ri * g.x; hv[j].y += yv[j].y * ri * g.y; hv[j].z += yv[j].z * ri * g.z; hv[j].w += yv[j].w * ri * g.w;
;       }
.LBB0_2737:
	v_lshl_add_u64 v[0:1], s[6:7], 0, v[18:19]
	global_load_dwordx2 v[2:3], v[0:1], off
	global_load_dwordx2 v[4:5], v[0:1], off offset:512
	global_load_dwordx2 v[6:7], v[0:1], off offset:1024
	global_load_dwordx2 v[32:33], v[0:1], off offset:1536
	s_and_b64 vcc, exec, s[0:1]
	s_waitcnt vmcnt(3)
	v_lshlrev_b32_e32 v12, 16, v2
	v_and_b32_e32 v13, 0xffff0000, v2
	v_lshlrev_b32_e32 v14, 16, v3
	v_and_b32_e32 v15, 0xffff0000, v3
	s_waitcnt vmcnt(2)
	v_lshlrev_b32_e32 v8, 16, v4
	v_and_b32_e32 v9, 0xffff0000, v4
	v_lshlrev_b32_e32 v10, 16, v5
	v_and_b32_e32 v11, 0xffff0000, v5
	s_waitcnt vmcnt(1)
	v_lshlrev_b32_e32 v4, 16, v6
	v_and_b32_e32 v5, 0xffff0000, v6
	v_lshlrev_b32_e32 v6, 16, v7
	v_and_b32_e32 v7, 0xffff0000, v7
	s_waitcnt vmcnt(0)
	v_lshlrev_b32_e32 v0, 16, v32
	v_and_b32_e32 v1, 0xffff0000, v32
	v_lshlrev_b32_e32 v2, 16, v33
	v_and_b32_e32 v3, 0xffff0000, v33
	s_cbranch_vccnz .LBB0_2739
	v_lshl_add_u64 v[32:33], s[4:5], 0, v[18:19]
	global_load_dwordx2 v[48:49], v[32:33], off
	global_load_dwordx2 v[50:51], v[32:33], off offset:512
	global_load_dwordx2 v[52:53], v[32:33], off offset:1024
	global_load_dwordx2 v[54:55], v[32:33], off offset:1536
	s_nop 0
	global_load_dwordx4 v[32:35], v[16:17], off
	global_load_dwordx4 v[36:39], v[16:17], off offset:1024
	global_load_dwordx4 v[40:43], v[16:17], off offset:2048
	global_load_dwordx4 v[44:47], v[16:17], off offset:3072
	v_cmp_lt_i32_e32 vcc, v26, v25
	s_waitcnt vmcnt(7)
	v_and_b32_e32 v57, 0xffff0000, v48
	v_cndmask_b32_e32 v56, v24, v26, vcc
	s_waitcnt vmcnt(6)
	v_and_b32_e32 v59, 0xffff0000, v50
	v_lshlrev_b32_e32 v80, 2, v56
	v_lshlrev_b32_e32 v56, 16, v48
	v_lshlrev_b32_e32 v58, 16, v50
	s_waitcnt vmcnt(5)
	v_and_b32_e32 v61, 0xffff0000, v52
	s_waitcnt vmcnt(4)
	v_and_b32_e32 v63, 0xffff0000, v54
	v_mov_b32_e32 v66, v57
	v_mov_b32_e32 v67, v59
	v_lshlrev_b32_e32 v48, 16, v49
	v_lshlrev_b32_e32 v50, 16, v51
	v_lshlrev_b32_e32 v60, 16, v52
	v_lshlrev_b32_e32 v62, 16, v54
	v_mov_b32_e32 v64, v56
	v_mov_b32_e32 v65, v58
	v_mov_b32_e32 v74, v61
	v_mov_b32_e32 v75, v63
	v_pk_mul_f32 v[66:67], v[66:67], v[66:67]
	v_and_b32_e32 v49, 0xffff0000, v49
	v_and_b32_e32 v51, 0xffff0000, v51
	v_lshlrev_b32_e32 v52, 16, v53
	v_lshlrev_b32_e32 v54, 16, v55
	v_mov_b32_e32 v68, v48
	v_mov_b32_e32 v69, v50
	v_mov_b32_e32 v72, v60
	v_mov_b32_e32 v73, v62
	v_pk_mul_f32 v[74:75], v[74:75], v[74:75]
	v_pk_fma_f32 v[64:65], v[64:65], v[64:65], v[66:67]
	v_and_b32_e32 v53, 0xffff0000, v53
	v_and_b32_e32 v55, 0xffff0000, v55
	v_mov_b32_e32 v70, v49
	v_mov_b32_e32 v71, v51
	v_mov_b32_e32 v76, v52
	v_mov_b32_e32 v77, v54
	v_pk_fma_f32 v[66:67], v[72:73], v[72:73], v[74:75]
	v_pk_fma_f32 v[64:65], v[68:69], v[68:69], v[64:65]
	v_mov_b32_e32 v78, v53
	v_mov_b32_e32 v79, v55
	v_pk_fma_f32 v[66:67], v[76:77], v[76:77], v[66:67]
	v_pk_fma_f32 v[64:65], v[70:71], v[70:71], v[64:65]
	v_pk_fma_f32 v[66:67], v[78:79], v[78:79], v[66:67]
	v_add_f32_e32 v64, v64, v65
	v_add_f32_e32 v64, v64, v66
	v_add_f32_e32 v64, v64, v67
	v_mov_b32_e32 v65, v64
	s_nop 1
	v_permlane32_swap_b32_e32 v65, v64
	v_add_f32_e32 v64, v64, v65
	v_mov_b32_e32 v65, v64
	s_nop 1
	v_permlane16_swap_b32_e32 v65, v64
	v_add_f32_e32 v64, v64, v65
	s_nop 1
	v_add_f32_dpp v64, v64, v64 row_ror:8 row_mask:0xf bank_mask:0xf
	s_nop 1
	v_add_f32_dpp v100, v64, v64 row_shl:4 row_mask:0xf bank_mask:0x5
	v_add_f32_dpp v100, v64, v64 row_shr:4 row_mask:0xf bank_mask:0xa
	s_nop 1
	v_add_f32_dpp v64, v100, v100 quad_perm:[2,3,0,1] row_mask:0xf bank_mask:0xf
	s_nop 1
	v_add_f32_dpp v64, v64, v64 quad_perm:[1,0,3,2] row_mask:0xf bank_mask:0xf
	s_waitcnt lgkmcnt(0)
	s_nop 0
	v_fmamk_f32 v64, v64, 0x3a800000, v23
	v_mul_f32_e32 v65, 0x4b800000, v64
	v_cmp_gt_f32_e32 vcc, s9, v64
	s_nop 1
	v_cndmask_b32_e32 v64, v64, v65, vcc
	v_rsq_f32_e32 v64, v64
	s_nop 0
	v_mul_f32_e32 v65, 0x45800000, v64
	v_cndmask_b32_e32 v64, v64, v65, vcc
	v_pk_mul_f32 v[56:57], v[64:65], v[56:57] op_sel_hi:[0,1]
	v_pk_mul_f32 v[48:49], v[64:65], v[48:49] op_sel_hi:[0,1]
	v_pk_mul_f32 v[58:59], v[64:65], v[58:59] op_sel_hi:[0,1]
	v_pk_mul_f32 v[50:51], v[64:65], v[50:51] op_sel_hi:[0,1]
	v_pk_mul_f32 v[60:61], v[64:65], v[60:61] op_sel_hi:[0,1]
	v_pk_mul_f32 v[52:53], v[64:65], v[52:53] op_sel_hi:[0,1]
	v_pk_mul_f32 v[62:63], v[64:65], v[62:63] op_sel_hi:[0,1]
	v_pk_mul_f32 v[54:55], v[64:65], v[54:55] op_sel_hi:[0,1]
	s_waitcnt vmcnt(3)
	v_pk_fma_f32 v[12:13], v[32:33], v[56:57], v[12:13]
	v_pk_fma_f32 v[14:15], v[34:35], v[48:49], v[14:15]
	s_waitcnt vmcnt(2)
	v_pk_fma_f32 v[8:9], v[36:37], v[58:59], v[8:9]
	v_pk_fma_f32 v[10:11], v[38:39], v[50:51], v[10:11]
	s_waitcnt vmcnt(1)
	v_pk_fma_f32 v[4:5], v[40:41], v[60:61], v[4:5]
	v_pk_fma_f32 v[6:7], v[42:43], v[52:53], v[6:7]
	s_waitcnt vmcnt(0)
	v_pk_fma_f32 v[0:1], v[44:45], v[62:63], v[0:1]
	v_pk_fma_f32 v[2:3], v[46:47], v[54:55], v[2:3]
